# split-K tail cut into 4 K-parts (quarter of the original atomic traffic, 16 k-tiles per part)
# baseline (speedup 1.0000x reference)
.LBB0_839:
	s_or_b64 exec, exec, s[0:1]
	v_cvt_f32_u32_e32 v0, s51
	s_sub_i32 s2, 0, s51
	s_abs_i32 s1, s33
	s_ashr_i32 s0, s33, 31
	s_waitcnt lgkmcnt(0)
	v_rcp_iflag_f32_e32 v1, v0
	v_mov_b32_e32 v0, v170
	s_mov_b32 s26, 1
	v_mul_f32_e32 v1, 0x4f7ffffe, v1
	v_cvt_u32_f32_e32 v1, v1
	s_barrier
	v_readfirstlane_b32 s3, v1
	s_mul_i32 s2, s2, s3
	s_mul_hi_u32 s2, s3, s2
	s_add_i32 s3, s3, s2
	s_mul_hi_u32 s2, s1, s3
	s_mul_i32 s2, s2, s51
	s_sub_i32 s1, s1, s2
	s_sub_i32 s2, s1, s51
	s_cmp_ge_u32 s1, s51
	s_cselect_b32 s1, s2, s1
	s_sub_i32 s2, s1, s51
	s_cmp_ge_u32 s1, s51
	s_cselect_b32 s1, s2, s1
	s_xor_b32 s1, s1, s0
	s_sub_i32 s0, s1, s0
	s_cmp_lt_i32 s0, 1
	s_cbranch_scc1 .LBB0_842
	v_cvt_f32_u32_e32 v1, s0
	s_sub_i32 s2, 0, s0
	s_mov_b32 s1, 1
	v_rcp_iflag_f32_e32 v1, v1
	s_nop 0
	v_mul_f32_e32 v1, 0x4f7ffffe, v1
	v_cvt_u32_f32_e32 v1, v1
	s_nop 0
	v_readfirstlane_b32 s3, v1
	s_mul_i32 s2, s2, s3
	s_mul_hi_u32 s2, s3, s2
	s_add_i32 s3, s3, s2
	s_mul_hi_u32 s2, s51, s3
	s_mul_i32 s3, s2, s0
	s_sub_i32 s3, s51, s3
	s_add_i32 s4, s2, 1
	s_sub_i32 s5, s3, s0
	s_cmp_ge_u32 s3, s0
	s_cselect_b32 s2, s4, s2
	s_cselect_b32 s3, s5, s3
	s_add_i32 s4, s2, 1
	s_cmp_ge_u32 s3, s0
	s_cselect_b32 s2, s4, s2
	s_min_u32 s2, s2, 4
